# P7|P8 seam: grid barrier replaced by a 4-workgroup group sync (the four WGs sharing a 256-row panel); HID stores are write-through
# speedup vs baseline: 1.0056x; 1.0056x over previous
; __device__ __forceinline__ unsigned xb_ld(unsigned* p)              { return __hip_atomic_load(p, __ATOMIC_RELAXED, __HIP_MEMORY_SCOPE_AGENT); }
; __device__ __forceinline__ unsigned xb_add(unsigned* p, unsigned v) { return __hip_atomic_fetch_add(p, v, __ATOMIC_RELAXED, __HIP_MEMORY_SCOPE_AGENT); }
; #define XB_SPIN(cond, bar) do { unsigned _sp = 0; while (cond) { __builtin_amdgcn_s_sleep(1); \
;     if ((++_sp & 255u) == 0u) { if (xb_ld(&(bar)[XB_TMO])) break; if (_sp > XB_SPIN_CAP) { atomicAdd(&(bar)[XB_TMO], 1u); break; } } } } while (0)
; __device__ __forceinline__ void xcd_barrier(const XcdBarrier& b) {
;     asm volatile("s_waitcnt vmcnt(0)" ::: "memory");
;     __syncthreads();
;     if (threadIdx.x == 0) {
;         unsigned* bar = b.bar;
;         __builtin_amdgcn_s_waitcnt(0);
;         unsigned nloc = b.st[0], nx = b.st[1];
;         if (nloc == 0u) { xcd_barrier_complete(bar, b.x, nloc, nx); b.st[0] = nloc; b.st[1] = nx; }
;         const unsigned old = xb_add(&bar[XB_XSUB(b.x)], 1u);
;         const unsigned gen = old / nloc;
;         if (old + 1u == (gen + 1u) * nloc) {
;             __builtin_amdgcn_fence(__ATOMIC_RELEASE, "agent");
;             asm volatile("s_waitcnt vmcnt(0)" ::: "memory");
;             const unsigned og = xb_add(&bar[XB_TOP], 1u);
;             const unsigned tg = og / nx;
;             __builtin_amdgcn_fence(__ATOMIC_ACQUIRE, "agent");
;             if (og + 1u == (tg + 1u) * nx) xb_add(&bar[XB_TOPGEN], 1u);
;             else XB_SPIN(xb_ld(&bar[XB_TOPGEN]) == tg, bar);
;             xb_add(&bar[XB_XGEN(b.x)], 1u);
;             asm volatile("s_waitcnt vmcnt(0)" ::: "memory");
;         } else {
;             __builtin_amdgcn_fence(__ATOMIC_ACQUIRE, "agent");
;             XB_SPIN(xb_ld(&bar[XB_XGEN(b.x)]) == gen, bar);
;             asm volatile("s_waitcnt vmcnt(0)" ::: "memory");
;         }
;     }
;     __syncthreads();
; }
.LBB0_865:
	s_waitcnt vmcnt(0)
	v_readlane_b32 s0, v253, 41
	v_readlane_b32 s1, v253, 42
	s_waitcnt vmcnt(0)
	s_barrier
	s_and_saveexec_b64 s[4:5], s[0:1]
	s_cbranch_execz .LBB0_917
	s_waitcnt vmcnt(0) lgkmcnt(0)
	v_readlane_b32 s8, v254, 29
	v_readlane_b32 s9, v254, 30
	v_readlane_b32 s20, v253, 0
	v_readlane_b32 s22, v254, 53
	s_add_u32 s8, s8, 0x2c00
	s_addc_u32 s9, s9, 0
	s_and_b32 s20, s20, 63
	s_lshl_b32 s20, s20, 8
	s_add_u32 s22, s22, 1
	s_lshl_b32 s22, s22, 2
	v_mov_b32_e32 v0, s20
	v_mov_b32_e32 v1, 1
	s_mov_b32 s25, 0
	s_nop 1
	global_atomic_add v0, v1, s[8:9]
	buffer_inv sc1
.Lgg_poll_4:
	global_load_dword v6, v0, s[8:9] sc1
	s_waitcnt vmcnt(0)
	v_readfirstlane_b32 s24, v6
	s_cmp_ge_u32 s24, s22
	s_cbranch_scc1 .Lgg_done_4
	s_sleep 1
	s_add_u32 s25, s25, 1
	s_cmp_lt_u32 s25, 0x8000
	s_cbranch_scc1 .Lgg_poll_4
